# P18: prep phase RoPE and V-transpose slices re-dealt across blocks by class (blocks with FNet step-1 tasks take fewer slices, blocks without take more); prep warm-up pre-loops removed
# speedup vs baseline: 1.0137x; 1.0137x over previous
.LBB0_502:
	s_or_b64 exec, exec, s[0:1]
	s_mov_b32 s0, 0x80000
	v_cmp_gt_i32_e32 vcc, s0, v164
	s_mov_b64 s[0:1], exec
	s_and_b64 s[18:19], s[0:1], vcc
	v_mov_b32_e32 v234, 1
	v_mov_b64_e32 v[236:237], 0x3bf
	v_mov_b64_e32 v[238:239], 0x3c0
	v_mov_b32_e32 v26, 0xfffff800
	v_mov_b32_e32 v27, 0xffffff00
	v_mov_b32_e32 v235, 0x80
	v_mov_b32_e32 v240, 0xbcb504f3
	v_mov_b32_e32 v241, 0x3cb504f3
	v_mov_b64_e32 v[242:243], 0x17f
	v_mov_b64_e32 v[244:245], 0x180
	s_mov_b64 exec, s[18:19]
	s_cbranch_execz .LBB0_505
	s_mul_i32 s18, s2, 1
	s_mov_b32 s19, 1
	s_cmp_lt_u32 s2, 2
	s_cbranch_scc1 .Ldeal_r_done
	s_cmp_lt_u32 s2, 0x80
	s_cbranch_scc0 .Ldeal_r_hi
	s_sub_i32 s18, s2, 2
	s_mul_i32 s18, s18, 3
	s_add_i32 s18, s18, 2
	s_mov_b32 s19, 3
	s_branch .Ldeal_r_done
.Ldeal_r_hi:
	s_cmp_lt_u32 s2, 0xe0
	s_cbranch_scc1 .Ldeal_r_idle
	s_sub_i32 s18, s2, 0xe0
	s_mul_i32 s18, s18, 1
	s_add_i32 s18, s18, 380
	s_mov_b32 s19, 1
	s_branch .Ldeal_r_done
.Ldeal_r_idle:
	s_sub_i32 s22, s2, 0x80
	s_mul_i32 s18, s22, 6
	s_min_u32 s19, s22, 36
	s_add_i32 s18, s18, s19
	s_add_i32 s18, s18, 412
	s_cmp_lt_u32 s22, 36
	s_cselect_b32 s19, 7, 6
.Ldeal_r_done:
	s_cmp_eq_u32 s19, 0
	s_cbranch_scc1 .LBB0_505
	s_add_i32 s19, s19, s18
	s_lshl_b32 s19, s19, 9
	s_add_i32 s19, s19, -1
	s_lshl_b32 s18, s18, 9
	s_mov_b64 s[28:29], 0
	v_add_u32_e32 v3, s18, v205
	v_lshlrev_b32_e32 v2, 3, v3
	v_lshlrev_b32_e32 v165, 4, v3
.LBB0_504:
	v_bfe_u32 v6, v3, 2, 1
	v_ashrrev_i32_e32 v0, 7, v3
	v_cmp_eq_u32_e32 vcc, 0, v6
	v_bfe_u32 v4, v0, 6, 5
	v_and_b32_e32 v5, 63, v0
	v_cndmask_b32_e32 v4, v5, v4, vcc
	v_cvt_f32_ubyte0_e32 v24, v4
	v_add_u32_e32 v0, 0x2000, v0
	v_mov_b64_e32 v[4:5], s[36:37]
	v_mad_i64_i32 v[4:5], s[22:23], v0, s77, v[4:5]
	v_and_b32_e32 v0, 0x780, v165
	v_lshlrev_b32_e32 v0, 1, v0
	v_lshl_add_u64 v[4:5], v[4:5], 0, v[0:1]
	v_lshlrev_b32_e32 v0, 7, v6
	v_and_b32_e32 v25, 24, v2
	v_lshl_add_u64 v[4:5], v[4:5], 0, v[0:1]
	v_lshlrev_b32_e32 v0, 1, v25
	v_lshl_add_u64 v[12:13], v[4:5], 0, v[0:1]
	flat_load_dwordx4 v[4:7], v[12:13]
	flat_load_dwordx4 v[8:11], v[12:13] offset:64
	v_cvt_f32_ubyte0_e32 v0, v25
	v_mul_f32_e32 v0, 0xbed49a78, v0
	v_exp_f32_e32 v0, v0
	v_add_u32_e32 v3, 0x200, v3
	s_mov_b32 s22, 0x7ffff
	v_cmp_lt_i32_e32 vcc, s19, v3
	v_mul_f32_e32 v0, v0, v24
	v_mul_f32_e32 v0, 0.15915494, v0
	v_cos_f32_e32 v14, v0
	v_sin_f32_e32 v16, v0
	v_or_b32_e32 v0, 1, v25
	v_cvt_f32_ubyte0_e32 v0, v0
	v_mul_f32_e32 v0, 0xbed49a78, v0
	v_exp_f32_e32 v0, v0
	v_add_u32_e32 v2, 0x1000, v2
	v_add_u32_e32 v165, 0x2000, v165
	s_or_b64 s[28:29], vcc, s[28:29]
	v_mul_f32_e32 v0, v0, v24
	v_mul_f32_e32 v0, 0.15915494, v0
	v_cos_f32_e32 v15, v0
	v_sin_f32_e32 v17, v0
	v_or_b32_e32 v0, 2, v25
	v_cvt_f32_ubyte0_e32 v0, v0
	v_mul_f32_e32 v0, 0xbed49a78, v0
	v_exp_f32_e32 v0, v0
	s_waitcnt vmcnt(0) lgkmcnt(0)
	v_lshlrev_b32_e32 v20, 16, v4
	v_lshlrev_b32_e32 v18, 16, v8
	v_and_b32_e32 v19, 0xffff0000, v8
	v_and_b32_e32 v21, 0xffff0000, v4
	v_pk_mul_f32 v[22:23], v[16:17], v[20:21]
	v_pk_mul_f32 v[16:17], v[16:17], v[18:19]
	v_mul_f32_e32 v0, v0, v24
	v_pk_fma_f32 v[22:23], v[14:15], v[18:19], v[22:23]
	v_pk_fma_f32 v[14:15], v[14:15], v[20:21], v[16:17] neg_lo:[0,0,1] neg_hi:[0,0,1]
	v_mul_f32_e32 v0, 0.15915494, v0
	v_cvt_pk_bf16_f32 v8, v14, v15
	v_cos_f32_e32 v14, v0
	v_sin_f32_e32 v16, v0
	v_or_b32_e32 v0, 3, v25
	v_cvt_f32_ubyte0_e32 v0, v0
	v_mul_f32_e32 v0, 0xbed49a78, v0
	v_exp_f32_e32 v0, v0
	v_lshlrev_b32_e32 v18, 16, v5
	v_and_b32_e32 v19, 0xffff0000, v5
	v_lshlrev_b32_e32 v20, 16, v9
	v_mul_f32_e32 v0, v0, v24
	v_mul_f32_e32 v0, 0.15915494, v0
	v_cos_f32_e32 v15, v0
	v_sin_f32_e32 v17, v0
	v_or_b32_e32 v0, 4, v25
	v_cvt_f32_ubyte0_e32 v0, v0
	v_mul_f32_e32 v0, 0xbed49a78, v0
	v_exp_f32_e32 v0, v0
	v_and_b32_e32 v21, 0xffff0000, v9
	v_cvt_pk_bf16_f32 v4, v22, v23
	v_pk_mul_f32 v[22:23], v[16:17], v[20:21]
	v_pk_mul_f32 v[16:17], v[16:17], v[18:19]
	v_mul_f32_e32 v0, v0, v24
	v_pk_fma_f32 v[22:23], v[14:15], v[18:19], v[22:23] neg_lo:[0,0,1] neg_hi:[0,0,1]
	v_pk_fma_f32 v[14:15], v[14:15], v[20:21], v[16:17]
	v_mul_f32_e32 v0, 0.15915494, v0
	v_cvt_pk_bf16_f32 v5, v14, v15
	v_cos_f32_e32 v14, v0
	v_sin_f32_e32 v16, v0
	v_or_b32_e32 v0, 5, v25
	v_cvt_f32_ubyte0_e32 v0, v0
	v_mul_f32_e32 v0, 0xbed49a78, v0
	v_exp_f32_e32 v0, v0
	v_lshlrev_b32_e32 v18, 16, v6
	v_and_b32_e32 v19, 0xffff0000, v6
	v_lshlrev_b32_e32 v20, 16, v10
	v_mul_f32_e32 v0, v0, v24
	v_mul_f32_e32 v0, 0.15915494, v0
	v_cos_f32_e32 v15, v0
	v_sin_f32_e32 v17, v0
	v_or_b32_e32 v0, 6, v25
	v_cvt_f32_ubyte0_e32 v0, v0
	v_mul_f32_e32 v0, 0xbed49a78, v0
	v_exp_f32_e32 v0, v0
	v_and_b32_e32 v21, 0xffff0000, v10
	v_cvt_pk_bf16_f32 v9, v22, v23
	v_pk_mul_f32 v[22:23], v[16:17], v[20:21]
	v_pk_mul_f32 v[16:17], v[16:17], v[18:19]
	v_mul_f32_e32 v0, v0, v24
	v_pk_fma_f32 v[22:23], v[14:15], v[18:19], v[22:23] neg_lo:[0,0,1] neg_hi:[0,0,1]
	v_pk_fma_f32 v[14:15], v[14:15], v[20:21], v[16:17]
	v_mul_f32_e32 v0, 0.15915494, v0
	v_cvt_pk_bf16_f32 v6, v14, v15
	v_cos_f32_e32 v14, v0
	v_sin_f32_e32 v16, v0
	v_or_b32_e32 v0, 7, v25
	v_cvt_f32_ubyte0_e32 v0, v0
	v_mul_f32_e32 v0, 0xbed49a78, v0
	v_exp_f32_e32 v0, v0
	v_lshlrev_b32_e32 v20, 16, v11
	v_and_b32_e32 v21, 0xffff0000, v11
	v_cvt_pk_bf16_f32 v10, v22, v23
	v_mul_f32_e32 v0, v0, v24
	v_mul_f32_e32 v0, 0.15915494, v0
	v_sin_f32_e32 v17, v0
	v_cos_f32_e32 v15, v0
	v_lshlrev_b32_e32 v18, 16, v7
	v_and_b32_e32 v19, 0xffff0000, v7
	v_pk_mul_f32 v[22:23], v[16:17], v[20:21]
	v_pk_mul_f32 v[16:17], v[16:17], v[18:19]
	v_pk_fma_f32 v[22:23], v[14:15], v[18:19], v[22:23] neg_lo:[0,0,1] neg_hi:[0,0,1]
	v_pk_fma_f32 v[14:15], v[14:15], v[20:21], v[16:17]
	v_cvt_pk_bf16_f32 v11, v22, v23
	v_cvt_pk_bf16_f32 v7, v14, v15
	flat_store_dwordx4 v[12:13], v[8:11]
	flat_store_dwordx4 v[12:13], v[4:7] offset:64
	s_andn2_b64 exec, exec, s[28:29]
	s_cbranch_execnz .LBB0_504
.LBB0_505:
	s_or_b64 exec, exec, s[0:1]
	s_mov_b32 s0, 0xc0000
	v_cmp_gt_i32_e32 vcc, s0, v164
	s_and_saveexec_b64 s[28:29], vcc
	s_movk_i32 s18, 0x6000
	s_movk_i32 s19, 0x3000
	s_mov_b32 s22, 0x10000
	s_cbranch_execz .LBB0_508
	s_add_u32 s24, s24, 0x1a848000
	s_addc_u32 s25, s25, 0
	v_and_b32_e32 v2, 0x1ff, v205
	v_mov_b32_e32 v3, v1
	s_mov_b64 s[30:31], 0
	s_mul_i32 s0, s2, 2
	s_mov_b32 s1, 2
	s_cmp_lt_u32 s2, 2
	s_cbranch_scc1 .Ldeal_v_done
	s_cmp_lt_u32 s2, 0x80
	s_cbranch_scc0 .Ldeal_v_hi
	s_sub_i32 s0, s2, 2
	s_mul_i32 s0, s0, 4
	s_add_i32 s0, s0, 4
	s_mov_b32 s1, 4
	s_branch .Ldeal_v_done
.Ldeal_v_hi:
	s_cmp_lt_u32 s2, 0xe0
	s_cbranch_scc1 .Ldeal_v_idle
	s_sub_i32 s0, s2, 0xe0
	s_mul_i32 s0, s0, 2
	s_add_i32 s0, s0, 508
	s_mov_b32 s1, 2
	s_branch .Ldeal_v_done
.Ldeal_v_idle:
	s_sub_i32 s18, s2, 0x80
	s_mul_i32 s0, s18, 10
	s_sub_i32 s1, s18, 92
	s_max_i32 s1, s1, 0
	s_add_i32 s0, s0, s1
	s_add_i32 s0, s0, 572
	s_cmp_ge_u32 s18, 92
	s_cselect_b32 s1, 11, 10
.Ldeal_v_done:
	s_cmp_eq_u32 s1, 0
	s_cbranch_scc1 .LBB0_508
	s_add_i32 s18, s0, s1
	s_lshl_b32 s18, s18, 9
	s_add_i32 s18, s18, -1
	s_lshl_b32 s0, s0, 9
	v_add_u32_e32 v164, s0, v205
.LBB0_507:
	v_ashrrev_i32_e32 v20, 6, v164
	v_mov_b64_e32 v[4:5], s[36:37]
	v_and_b32_e32 v21, -8, v20
	v_lshlrev_b32_e32 v0, 1, v2
	v_mad_i64_i32 v[4:5], s[0:1], v21, s77, v[4:5]
	v_lshl_add_u64 v[4:5], v[4:5], 0, v[0:1]
	s_mov_b32 s0, 0xb000
	v_add_co_u32_e64 v8, s[0:1], s0, v4
	v_add_co_u32_e32 v6, vcc, 0x1000, v4
	s_nop 0
	v_addc_co_u32_e64 v9, s[0:1], 0, v5, s[0:1]
	s_mov_b32 s0, 0xd000
	s_nop 0
	v_add_co_u32_e64 v10, s[0:1], s0, v4
	v_addc_co_u32_e32 v7, vcc, 0, v5, vcc
	s_nop 0
	v_addc_co_u32_e64 v11, s[0:1], 0, v5, s[0:1]
	v_add_co_u32_e64 v12, s[0:1], s22, v4
	v_add_co_u32_e32 v16, vcc, s19, v4
	s_nop 0
	v_addc_co_u32_e64 v13, s[0:1], 0, v5, s[0:1]
	s_mov_b32 s0, 0x12000
	s_nop 0
	v_add_co_u32_e64 v14, s[0:1], s0, v4
	v_addc_co_u32_e32 v17, vcc, 0, v5, vcc
	s_nop 0
	v_addc_co_u32_e64 v15, s[0:1], 0, v5, s[0:1]
	v_add_co_u32_e32 v18, vcc, 0x6000, v4
	s_mov_b32 s0, 0x8000
	s_nop 0
	v_addc_co_u32_e32 v19, vcc, 0, v5, vcc
	v_add_co_u32_e32 v4, vcc, s0, v4
	flat_load_ushort v0, v[6:7]
	s_nop 0
	flat_load_ushort v16, v[16:17] offset:2048
	v_addc_co_u32_e32 v5, vcc, 0, v5, vcc
	flat_load_ushort v17, v[18:19]
	s_nop 0
	flat_load_ushort v18, v[4:5] offset:2048
	flat_load_ushort v19, v[8:9]
	s_nop 0
	flat_load_ushort v10, v[10:11] offset:2048
	s_nop 0
	flat_load_ushort v11, v[12:13]
	s_nop 0
	flat_load_ushort v12, v[14:15] offset:2048
	v_add_u32_e32 v164, 0x200, v164
	s_mov_b32 s0, 0xbffff
	v_cmp_lt_i32_e32 vcc, s18, v164
	v_cmp_gt_i32_e64 s[0:1], s34, v21
	s_or_b64 s[30:31], vcc, s[30:31]
	s_nop 0
	v_cndmask_b32_e64 v4, v26, v27, s[0:1]
	v_and_b32_e32 v4, v4, v20
	v_ashrrev_i32_e32 v5, 31, v4
	v_cndmask_b32_e64 v6, 11, 8, s[0:1]
	v_sub_u32_e32 v8, v21, v4
	v_lshlrev_b64 v[4:5], 10, v[4:5]
	v_lshlrev_b64 v[6:7], v6, v[2:3]
	v_lshl_add_u64 v[4:5], s[24:25], 0, v[4:5]
	v_ashrrev_i32_e32 v9, 31, v8
	v_lshl_add_u64 v[4:5], v[6:7], 1, v[4:5]
	v_lshl_add_u64 v[8:9], v[8:9], 1, v[4:5]
	s_waitcnt vmcnt(0) lgkmcnt(0)
	v_lshl_or_b32 v5, v18, 16, v17
	v_lshl_or_b32 v4, v16, 16, v0
	v_lshl_or_b32 v6, v10, 16, v19
	v_lshl_or_b32 v7, v12, 16, v11
	flat_store_dwordx4 v[8:9], v[4:7]
	s_andn2_b64 exec, exec, s[30:31]
	s_cbranch_execnz .LBB0_507
